# mini-GEMM K-loop: fragment ds_reads issued before the LDS-DMA stage loads (on top of v23)
# speedup vs baseline: 1.0077x; 1.0019x over previous
; __device__ __forceinline__ void mini_gemm(PG8_LAS unsigned char* lds, const bf16_t* A, const bf16_t* Bt, bf16_t* O, int ldc, int N, int blk, int G, const int tid) {
;     ...
;         for (int kt = 0; kt < NKT - 3; ++kt) {
;             asm volatile("s_waitcnt vmcnt(8)" ::: "memory"); __builtin_amdgcn_s_barrier(); __builtin_amdgcn_sched_barrier(0);
;             MG_STAGE((kt + 3) & 3, kt + 3);
;             MG_COMPUTE(kt & 3);
;         }
;         asm volatile("s_waitcnt vmcnt(8)" ::: "memory"); __builtin_amdgcn_s_barrier(); __builtin_amdgcn_sched_barrier(0); MG_COMPUTE((NKT - 3) & 3);
;         asm volatile("s_waitcnt vmcnt(4)" ::: "memory"); __builtin_amdgcn_s_barrier(); __builtin_amdgcn_sched_barrier(0); MG_COMPUTE((NKT - 2) & 3);
.LBB0_68:
	s_waitcnt vmcnt(8)
	s_barrier
	s_and_b32 s9, s3, 0x18000
	v_add_u32_e32 v66, s9, v52
	v_add_u32_e32 v98, s9, v51
	ds_read_b128 v[54:57], v66 offset:16384
	ds_read_b128 v[58:61], v66 offset:17408
	ds_read_b128 v[62:65], v66 offset:18432
	ds_read_b128 v[66:69], v66 offset:19456
	ds_read_b128 v[70:73], v98
	ds_read_b128 v[74:77], v98 offset:1024
	ds_read_b128 v[78:81], v98 offset:2048
	ds_read_b128 v[82:85], v98 offset:3072
	ds_read_b128 v[86:89], v98 offset:4096
	ds_read_b128 v[90:93], v98 offset:5120
	ds_read_b128 v[94:97], v98 offset:6144
	ds_read_b128 v[98:101], v98 offset:7168
	s_add_i32 s9, s3, 0x18000
	s_and_b32 s9, s9, 0x18000
	s_add_i32 s9, s6, s9
	s_add_i32 s10, s9, 0x4000
	v_lshl_add_u64 v[102:103], v[42:43], 0, s[4:5]
	s_mov_b32 m0, s9
	s_nop 0
	global_load_lds_dwordx4 v[102:103], off
	v_lshl_add_u64 v[102:103], v[46:47], 0, s[4:5]
	s_mov_b32 m0, s10
	s_nop 0
	global_load_lds_dwordx4 v[102:103], off
	v_lshl_add_u64 v[102:103], v[44:45], 0, s[4:5]
	s_add_i32 m0, s9, 0x2000
	s_nop 0
	global_load_lds_dwordx4 v[102:103], off
	v_lshl_add_u64 v[102:103], v[48:49], 0, s[4:5]
	s_add_i32 m0, s9, 0x6000
	s_nop 0
	global_load_lds_dwordx4 v[102:103], off
	s_waitcnt lgkmcnt(0)
	s_waitcnt lgkmcnt(0)
	v_mfma_f32_16x16x32_bf16 v[2:5], v[54:57], v[70:73], v[2:5]
	v_mfma_f32_16x16x32_bf16 v[6:9], v[62:65], v[70:73], v[6:9]
	v_mfma_f32_16x16x32_bf16 v[10:13], v[54:57], v[78:81], v[10:13]
	v_mfma_f32_16x16x32_bf16 v[14:17], v[62:65], v[78:81], v[14:17]
	v_mfma_f32_16x16x32_bf16 v[18:21], v[54:57], v[86:89], v[18:21]
	v_mfma_f32_16x16x32_bf16 v[22:25], v[62:65], v[86:89], v[22:25]
	v_mfma_f32_16x16x32_bf16 v[26:29], v[54:57], v[94:97], v[26:29]
	v_mfma_f32_16x16x32_bf16 v[30:33], v[62:65], v[94:97], v[30:33]
	v_mfma_f32_16x16x32_bf16 v[2:5], v[58:61], v[74:77], v[2:5]
	v_mfma_f32_16x16x32_bf16 v[6:9], v[66:69], v[74:77], v[6:9]
	v_mfma_f32_16x16x32_bf16 v[10:13], v[58:61], v[82:85], v[10:13]
	v_mfma_f32_16x16x32_bf16 v[14:17], v[66:69], v[82:85], v[14:17]
	v_mfma_f32_16x16x32_bf16 v[18:21], v[58:61], v[90:93], v[18:21]
	v_mfma_f32_16x16x32_bf16 v[22:25], v[66:69], v[90:93], v[22:25]
	v_mfma_f32_16x16x32_bf16 v[26:29], v[58:61], v[98:101], v[26:29]
	v_mfma_f32_16x16x32_bf16 v[30:33], v[66:69], v[98:101], v[30:33]
	s_add_u32 s4, s4, 0x80
	s_addc_u32 s5, s5, 0
	s_add_i32 s3, s3, 0x8000
	s_cmpk_eq_i32 s4, 0xe80
	s_cbranch_scc0 .LBB0_68
	s_waitcnt vmcnt(8)
	s_barrier
	ds_read_b128 v[42:45], v52 offset:49152
	ds_read_b128 v[46:49], v52 offset:50176
	ds_read_b128 v[54:57], v52 offset:51200
	ds_read_b128 v[58:61], v52 offset:52224
	ds_read_b128 v[62:65], v51 offset:32768
	ds_read_b128 v[66:69], v51 offset:33792
	ds_read_b128 v[70:73], v51 offset:34816
	ds_read_b128 v[74:77], v51 offset:35840
	ds_read_b128 v[78:81], v51 offset:36864
	ds_read_b128 v[82:85], v51 offset:37888
	ds_read_b128 v[86:89], v51 offset:38912
	ds_read_b128 v[90:93], v51 offset:39936
	s_waitcnt lgkmcnt(0)
	s_waitcnt lgkmcnt(0)
	v_mfma_f32_16x16x32_bf16 v[2:5], v[42:45], v[62:65], v[2:5]
	v_mfma_f32_16x16x32_bf16 v[6:9], v[54:57], v[62:65], v[6:9]
	v_mfma_f32_16x16x32_bf16 v[10:13], v[42:45], v[70:73], v[10:13]
	v_mfma_f32_16x16x32_bf16 v[14:17], v[54:57], v[70:73], v[14:17]
	v_mfma_f32_16x16x32_bf16 v[18:21], v[42:45], v[78:81], v[18:21]
	v_mfma_f32_16x16x32_bf16 v[22:25], v[54:57], v[78:81], v[22:25]
	v_mfma_f32_16x16x32_bf16 v[26:29], v[42:45], v[86:89], v[26:29]
	v_mfma_f32_16x16x32_bf16 v[30:33], v[54:57], v[86:89], v[30:33]
	v_mfma_f32_16x16x32_bf16 v[2:5], v[46:49], v[66:69], v[2:5]
	v_mfma_f32_16x16x32_bf16 v[6:9], v[58:61], v[66:69], v[6:9]
	v_mfma_f32_16x16x32_bf16 v[10:13], v[46:49], v[74:77], v[10:13]
	v_mfma_f32_16x16x32_bf16 v[14:17], v[58:61], v[74:77], v[14:17]
	v_mfma_f32_16x16x32_bf16 v[18:21], v[46:49], v[82:85], v[18:21]
	v_mfma_f32_16x16x32_bf16 v[22:25], v[58:61], v[82:85], v[22:25]
	v_mfma_f32_16x16x32_bf16 v[26:29], v[46:49], v[90:93], v[26:29]
	v_mfma_f32_16x16x32_bf16 v[30:33], v[58:61], v[90:93], v[30:33]
	s_waitcnt vmcnt(4)
	s_barrier
; __device__ __forceinline__ unsigned pk2(float lo, float hi) { f32x2 v = {lo, hi}; hbf2 b = __builtin_convertvector(v, hbf2); return __builtin_bit_cast(unsigned, b); }
; __device__ __forceinline__ void mini_gemm(PG8_LAS unsigned char* lds, const bf16_t* A, const bf16_t* Bt, bf16_t* O, int ldc, int N, int blk, int G, const int tid) {
;     ...
;         asm volatile("s_waitcnt vmcnt(4)" ::: "memory"); __builtin_amdgcn_s_barrier(); __builtin_amdgcn_sched_barrier(0); MG_COMPUTE((NKT - 2) & 3);
;         asm volatile("s_waitcnt vmcnt(0)" ::: "memory"); __builtin_amdgcn_s_barrier(); __builtin_amdgcn_sched_barrier(0); MG_COMPUTE((NKT - 1) & 3);
;         const int row0 = tm * 128 + wr * 64 + fr, col0 = tn * 128 + wc * 32 + 8 * fq;
; #pragma unroll
;         for (int m = 0; m < 4; ++m) { const f32x4 v0 = acc[m][0], v1 = acc[m][1]; u32x4 w; w.x = pk2(v0[0], v0[1]); w.y = pk2(v0[2], v0[3]); w.z = pk2(v1[0], v1[1]); w.w = pk2(v1[2], v1[3]);
;             *(u32x4*)(O + (size_t)(row0 + m * 16) * ldc + col0) = w; }
;         __builtin_amdgcn_s_barrier();
;     }
	v_add_u32_e32 v58, 0x14000, v52
	v_add_u32_e32 v90, 0x10000, v51
	ds_read_b128 v[42:45], v58
	ds_read_b128 v[46:49], v58 offset:1024
	ds_read_b128 v[54:57], v58 offset:2048
	ds_read_b128 v[58:61], v58 offset:3072
	ds_read_b128 v[62:65], v90
	ds_read_b128 v[66:69], v90 offset:1024
	ds_read_b128 v[70:73], v90 offset:2048
	ds_read_b128 v[74:77], v90 offset:3072
	ds_read_b128 v[78:81], v90 offset:4096
	ds_read_b128 v[82:85], v90 offset:5120
	ds_read_b128 v[86:89], v90 offset:6144
	ds_read_b128 v[90:93], v90 offset:7168
	s_waitcnt lgkmcnt(0)
	s_waitcnt lgkmcnt(0)
	v_mfma_f32_16x16x32_bf16 v[2:5], v[42:45], v[62:65], v[2:5]
	v_mfma_f32_16x16x32_bf16 v[6:9], v[54:57], v[62:65], v[6:9]
	v_mfma_f32_16x16x32_bf16 v[10:13], v[42:45], v[70:73], v[10:13]
	v_mfma_f32_16x16x32_bf16 v[14:17], v[54:57], v[70:73], v[14:17]
	v_mfma_f32_16x16x32_bf16 v[18:21], v[42:45], v[78:81], v[18:21]
	v_mfma_f32_16x16x32_bf16 v[22:25], v[54:57], v[78:81], v[22:25]
	v_mfma_f32_16x16x32_bf16 v[26:29], v[42:45], v[86:89], v[26:29]
	v_mfma_f32_16x16x32_bf16 v[30:33], v[54:57], v[86:89], v[30:33]
	v_mfma_f32_16x16x32_bf16 v[2:5], v[46:49], v[66:69], v[2:5]
	v_mfma_f32_16x16x32_bf16 v[6:9], v[58:61], v[66:69], v[6:9]
	v_mfma_f32_16x16x32_bf16 v[10:13], v[46:49], v[74:77], v[10:13]
	v_mfma_f32_16x16x32_bf16 v[14:17], v[58:61], v[74:77], v[14:17]
	v_mfma_f32_16x16x32_bf16 v[18:21], v[46:49], v[82:85], v[18:21]
	v_mfma_f32_16x16x32_bf16 v[22:25], v[58:61], v[82:85], v[22:25]
	v_mfma_f32_16x16x32_bf16 v[26:29], v[46:49], v[90:93], v[26:29]
	v_mfma_f32_16x16x32_bf16 v[30:33], v[58:61], v[90:93], v[30:33]
	s_waitcnt vmcnt(0)
	s_barrier
	v_add_u32_e32 v58, 0x1c000, v52
	v_add_u32_e32 v90, 0x18000, v51
	ds_read_b128 v[42:45], v58
	ds_read_b128 v[46:49], v58 offset:1024
	ds_read_b128 v[54:57], v58 offset:2048
	ds_read_b128 v[58:61], v58 offset:3072
	ds_read_b128 v[62:65], v90
	ds_read_b128 v[66:69], v90 offset:1024
	ds_read_b128 v[70:73], v90 offset:2048
	ds_read_b128 v[74:77], v90 offset:3072
	ds_read_b128 v[78:81], v90 offset:4096
	ds_read_b128 v[82:85], v90 offset:5120
	ds_read_b128 v[86:89], v90 offset:6144
	ds_read_b128 v[90:93], v90 offset:7168
	s_waitcnt lgkmcnt(0)
	s_waitcnt lgkmcnt(0)
	v_mfma_f32_16x16x32_bf16 v[2:5], v[42:45], v[62:65], v[2:5]
	v_mfma_f32_16x16x32_bf16 v[6:9], v[54:57], v[62:65], v[6:9]
	v_mfma_f32_16x16x32_bf16 v[10:13], v[42:45], v[70:73], v[10:13]
	v_mfma_f32_16x16x32_bf16 v[14:17], v[54:57], v[70:73], v[14:17]
	v_mfma_f32_16x16x32_bf16 v[18:21], v[42:45], v[78:81], v[18:21]
	v_mfma_f32_16x16x32_bf16 v[22:25], v[54:57], v[78:81], v[22:25]
	v_mfma_f32_16x16x32_bf16 v[26:29], v[42:45], v[86:89], v[26:29]
	v_mfma_f32_16x16x32_bf16 v[30:33], v[54:57], v[86:89], v[30:33]
	v_mfma_f32_16x16x32_bf16 v[2:5], v[46:49], v[66:69], v[2:5]
	v_mfma_f32_16x16x32_bf16 v[6:9], v[58:61], v[66:69], v[6:9]
	v_mfma_f32_16x16x32_bf16 v[10:13], v[46:49], v[74:77], v[10:13]
	v_mfma_f32_16x16x32_bf16 v[14:17], v[58:61], v[74:77], v[14:17]
	v_mfma_f32_16x16x32_bf16 v[18:21], v[46:49], v[82:85], v[18:21]
	v_mfma_f32_16x16x32_bf16 v[22:25], v[58:61], v[82:85], v[22:25]
	v_mfma_f32_16x16x32_bf16 v[26:29], v[46:49], v[90:93], v[26:29]
	v_mfma_f32_16x16x32_bf16 v[30:33], v[58:61], v[90:93], v[30:33]
	v_lshl_or_b32 v42, s2, 7, v53
	v_lshl_add_u32 v44, s8, 7, v50
	v_ashrrev_i32_e32 v43, 31, v42
	v_ashrrev_i32_e32 v45, 31, v44
	v_lshl_add_u64 v[42:43], v[42:43], 1, s[60:61]
	v_cvt_pk_bf16_f32 v2, v2, v3
	v_cvt_pk_bf16_f32 v3, v4, v5
	v_cvt_pk_bf16_f32 v4, v6, v7
	v_lshlrev_b64 v[6:7], 14, v[44:45]
	v_cvt_pk_bf16_f32 v5, v8, v9
	v_lshl_add_u64 v[6:7], v[42:43], 0, v[6:7]
	global_store_dwordx4 v[6:7], v[2:5], off
	v_or_b32_e32 v6, 16, v44
	v_ashrrev_i32_e32 v7, 31, v6
	v_lshlrev_b64 v[6:7], 14, v[6:7]
	v_cvt_pk_bf16_f32 v2, v10, v11
	v_cvt_pk_bf16_f32 v3, v12, v13
	v_cvt_pk_bf16_f32 v4, v14, v15
	v_cvt_pk_bf16_f32 v5, v16, v17
	v_lshl_add_u64 v[6:7], v[42:43], 0, v[6:7]
	global_store_dwordx4 v[6:7], v[2:5], off
	v_or_b32_e32 v6, 32, v44
	v_ashrrev_i32_e32 v7, 31, v6
	v_lshlrev_b64 v[6:7], 14, v[6:7]
	v_cvt_pk_bf16_f32 v2, v18, v19
	v_cvt_pk_bf16_f32 v3, v20, v21
	v_cvt_pk_bf16_f32 v4, v22, v23
	v_cvt_pk_bf16_f32 v5, v24, v25
	v_lshl_add_u64 v[6:7], v[42:43], 0, v[6:7]
	global_store_dwordx4 v[6:7], v[2:5], off
	v_or_b32_e32 v6, 48, v44
	v_ashrrev_i32_e32 v7, 31, v6
	v_lshlrev_b64 v[6:7], 14, v[6:7]
	s_add_i32 s7, s7, s20
	s_add_i32 s21, s21, s20
	v_cvt_pk_bf16_f32 v2, v26, v27
	v_cvt_pk_bf16_f32 v3, v28, v29
	v_cvt_pk_bf16_f32 v4, v30, v31
	v_cvt_pk_bf16_f32 v5, v32, v33
	v_lshl_add_u64 v[6:7], v[42:43], 0, v[6:7]
	s_cmpk_gt_i32 s7, 0xff
	global_store_dwordx4 v[6:7], v[2:5], off
	s_barrier
	s_cbranch_scc0 .LBB0_67

; __device__ __forceinline__ void mini_gemm(PG8_LAS unsigned char* lds, const bf16_t* A, const bf16_t* Bt, bf16_t* O, int ldc, int N, int blk, int G, const int tid) {
;     ...
;         for (int kt = 0; kt < NKT - 3; ++kt) {
;             asm volatile("s_waitcnt vmcnt(8)" ::: "memory"); __builtin_amdgcn_s_barrier(); __builtin_amdgcn_sched_barrier(0);
;             MG_STAGE((kt + 3) & 3, kt + 3);
;             MG_COMPUTE(kt & 3);
;         }
;         asm volatile("s_waitcnt vmcnt(8)" ::: "memory"); __builtin_amdgcn_s_barrier(); __builtin_amdgcn_sched_barrier(0); MG_COMPUTE((NKT - 3) & 3);
;         asm volatile("s_waitcnt vmcnt(4)" ::: "memory"); __builtin_amdgcn_s_barrier(); __builtin_amdgcn_sched_barrier(0); MG_COMPUTE((NKT - 2) & 3);
.LBB0_504:
	s_waitcnt vmcnt(8)
	s_barrier
	s_and_b32 s9, s3, 0x18000
	v_add_u32_e32 v66, s9, v52
	v_add_u32_e32 v98, s9, v51
	ds_read_b128 v[54:57], v66 offset:16384
	ds_read_b128 v[58:61], v66 offset:17408
	ds_read_b128 v[62:65], v66 offset:18432
	ds_read_b128 v[66:69], v66 offset:19456
	ds_read_b128 v[70:73], v98
	ds_read_b128 v[74:77], v98 offset:1024
	ds_read_b128 v[78:81], v98 offset:2048
	ds_read_b128 v[82:85], v98 offset:3072
	ds_read_b128 v[86:89], v98 offset:4096
	ds_read_b128 v[90:93], v98 offset:5120
	ds_read_b128 v[94:97], v98 offset:6144
	ds_read_b128 v[98:101], v98 offset:7168
	s_add_i32 s9, s3, 0x18000
	s_and_b32 s9, s9, 0x18000
	s_add_i32 s9, s6, s9
	s_add_i32 s10, s9, 0x4000
	v_lshl_add_u64 v[102:103], v[42:43], 0, s[4:5]
	s_mov_b32 m0, s9
	s_nop 0
	global_load_lds_dwordx4 v[102:103], off
	v_lshl_add_u64 v[102:103], v[46:47], 0, s[4:5]
	s_mov_b32 m0, s10
	s_nop 0
	global_load_lds_dwordx4 v[102:103], off
	v_lshl_add_u64 v[102:103], v[44:45], 0, s[4:5]
	s_add_i32 m0, s9, 0x2000
	s_nop 0
	global_load_lds_dwordx4 v[102:103], off
	v_lshl_add_u64 v[102:103], v[48:49], 0, s[4:5]
	s_add_i32 m0, s9, 0x6000
	s_nop 0
	global_load_lds_dwordx4 v[102:103], off
	s_waitcnt lgkmcnt(0)
	s_waitcnt lgkmcnt(0)
	v_mfma_f32_16x16x32_bf16 v[2:5], v[54:57], v[70:73], v[2:5]
	v_mfma_f32_16x16x32_bf16 v[6:9], v[62:65], v[70:73], v[6:9]
	v_mfma_f32_16x16x32_bf16 v[10:13], v[54:57], v[78:81], v[10:13]
	v_mfma_f32_16x16x32_bf16 v[14:17], v[62:65], v[78:81], v[14:17]
	v_mfma_f32_16x16x32_bf16 v[18:21], v[54:57], v[86:89], v[18:21]
	v_mfma_f32_16x16x32_bf16 v[22:25], v[62:65], v[86:89], v[22:25]
	v_mfma_f32_16x16x32_bf16 v[26:29], v[54:57], v[94:97], v[26:29]
	v_mfma_f32_16x16x32_bf16 v[30:33], v[62:65], v[94:97], v[30:33]
	v_mfma_f32_16x16x32_bf16 v[2:5], v[58:61], v[74:77], v[2:5]
	v_mfma_f32_16x16x32_bf16 v[6:9], v[66:69], v[74:77], v[6:9]
	v_mfma_f32_16x16x32_bf16 v[10:13], v[58:61], v[82:85], v[10:13]
	v_mfma_f32_16x16x32_bf16 v[14:17], v[66:69], v[82:85], v[14:17]
	v_mfma_f32_16x16x32_bf16 v[18:21], v[58:61], v[90:93], v[18:21]
	v_mfma_f32_16x16x32_bf16 v[22:25], v[66:69], v[90:93], v[22:25]
	v_mfma_f32_16x16x32_bf16 v[26:29], v[58:61], v[98:101], v[26:29]
	v_mfma_f32_16x16x32_bf16 v[30:33], v[66:69], v[98:101], v[30:33]
	s_add_u32 s4, s4, 0x80
	s_addc_u32 s5, s5, 0
	s_add_i32 s3, s3, 0x8000
	s_cmpk_eq_i32 s4, 0xe80
	s_cbranch_scc0 .LBB0_504
	s_waitcnt vmcnt(8)
	s_barrier
	ds_read_b128 v[42:45], v52 offset:49152
	ds_read_b128 v[46:49], v52 offset:50176
	ds_read_b128 v[54:57], v52 offset:51200
	ds_read_b128 v[58:61], v52 offset:52224
	ds_read_b128 v[62:65], v51 offset:32768
	ds_read_b128 v[66:69], v51 offset:33792
	ds_read_b128 v[70:73], v51 offset:34816
	ds_read_b128 v[74:77], v51 offset:35840
	ds_read_b128 v[78:81], v51 offset:36864
	ds_read_b128 v[82:85], v51 offset:37888
	ds_read_b128 v[86:89], v51 offset:38912
	ds_read_b128 v[90:93], v51 offset:39936
	s_waitcnt lgkmcnt(0)
	s_waitcnt lgkmcnt(0)
	v_mfma_f32_16x16x32_bf16 v[2:5], v[42:45], v[62:65], v[2:5]
	v_mfma_f32_16x16x32_bf16 v[6:9], v[54:57], v[62:65], v[6:9]
	v_mfma_f32_16x16x32_bf16 v[10:13], v[42:45], v[70:73], v[10:13]
	v_mfma_f32_16x16x32_bf16 v[14:17], v[54:57], v[70:73], v[14:17]
	v_mfma_f32_16x16x32_bf16 v[18:21], v[42:45], v[78:81], v[18:21]
	v_mfma_f32_16x16x32_bf16 v[22:25], v[54:57], v[78:81], v[22:25]
	v_mfma_f32_16x16x32_bf16 v[26:29], v[42:45], v[86:89], v[26:29]
	v_mfma_f32_16x16x32_bf16 v[30:33], v[54:57], v[86:89], v[30:33]
	v_mfma_f32_16x16x32_bf16 v[2:5], v[46:49], v[66:69], v[2:5]
	v_mfma_f32_16x16x32_bf16 v[6:9], v[58:61], v[66:69], v[6:9]
	v_mfma_f32_16x16x32_bf16 v[10:13], v[46:49], v[74:77], v[10:13]
	v_mfma_f32_16x16x32_bf16 v[14:17], v[58:61], v[74:77], v[14:17]
	v_mfma_f32_16x16x32_bf16 v[18:21], v[46:49], v[82:85], v[18:21]
	v_mfma_f32_16x16x32_bf16 v[22:25], v[58:61], v[82:85], v[22:25]
	v_mfma_f32_16x16x32_bf16 v[26:29], v[46:49], v[90:93], v[26:29]
	v_mfma_f32_16x16x32_bf16 v[30:33], v[58:61], v[90:93], v[30:33]
	s_waitcnt vmcnt(4)
	s_barrier
; __device__ __forceinline__ unsigned pk2(float lo, float hi) { f32x2 v = {lo, hi}; hbf2 b = __builtin_convertvector(v, hbf2); return __builtin_bit_cast(unsigned, b); }
; __device__ __forceinline__ void mini_gemm(PG8_LAS unsigned char* lds, const bf16_t* A, const bf16_t* Bt, bf16_t* O, int ldc, int N, int blk, int G, const int tid) {
;     ...
;         asm volatile("s_waitcnt vmcnt(4)" ::: "memory"); __builtin_amdgcn_s_barrier(); __builtin_amdgcn_sched_barrier(0); MG_COMPUTE((NKT - 2) & 3);
;         asm volatile("s_waitcnt vmcnt(0)" ::: "memory"); __builtin_amdgcn_s_barrier(); __builtin_amdgcn_sched_barrier(0); MG_COMPUTE((NKT - 1) & 3);
;         const int row0 = tm * 128 + wr * 64 + fr, col0 = tn * 128 + wc * 32 + 8 * fq;
; #pragma unroll
;         for (int m = 0; m < 4; ++m) { const f32x4 v0 = acc[m][0], v1 = acc[m][1]; u32x4 w; w.x = pk2(v0[0], v0[1]); w.y = pk2(v0[2], v0[3]); w.z = pk2(v1[0], v1[1]); w.w = pk2(v1[2], v1[3]);
;             *(u32x4*)(O + (size_t)(row0 + m * 16) * ldc + col0) = w; }
;         __builtin_amdgcn_s_barrier();
;     }
	v_add_u32_e32 v58, 0x14000, v52
	v_add_u32_e32 v90, 0x10000, v51
	ds_read_b128 v[42:45], v58
	ds_read_b128 v[46:49], v58 offset:1024
	ds_read_b128 v[54:57], v58 offset:2048
	ds_read_b128 v[58:61], v58 offset:3072
	ds_read_b128 v[62:65], v90
	ds_read_b128 v[66:69], v90 offset:1024
	ds_read_b128 v[70:73], v90 offset:2048
	ds_read_b128 v[74:77], v90 offset:3072
	ds_read_b128 v[78:81], v90 offset:4096
	ds_read_b128 v[82:85], v90 offset:5120
	ds_read_b128 v[86:89], v90 offset:6144
	ds_read_b128 v[90:93], v90 offset:7168
	s_waitcnt lgkmcnt(0)
	s_waitcnt lgkmcnt(0)
	v_mfma_f32_16x16x32_bf16 v[2:5], v[42:45], v[62:65], v[2:5]
	v_mfma_f32_16x16x32_bf16 v[6:9], v[54:57], v[62:65], v[6:9]
	v_mfma_f32_16x16x32_bf16 v[10:13], v[42:45], v[70:73], v[10:13]
	v_mfma_f32_16x16x32_bf16 v[14:17], v[54:57], v[70:73], v[14:17]
	v_mfma_f32_16x16x32_bf16 v[18:21], v[42:45], v[78:81], v[18:21]
	v_mfma_f32_16x16x32_bf16 v[22:25], v[54:57], v[78:81], v[22:25]
	v_mfma_f32_16x16x32_bf16 v[26:29], v[42:45], v[86:89], v[26:29]
	v_mfma_f32_16x16x32_bf16 v[30:33], v[54:57], v[86:89], v[30:33]
	v_mfma_f32_16x16x32_bf16 v[2:5], v[46:49], v[66:69], v[2:5]
	v_mfma_f32_16x16x32_bf16 v[6:9], v[58:61], v[66:69], v[6:9]
	v_mfma_f32_16x16x32_bf16 v[10:13], v[46:49], v[74:77], v[10:13]
	v_mfma_f32_16x16x32_bf16 v[14:17], v[58:61], v[74:77], v[14:17]
	v_mfma_f32_16x16x32_bf16 v[18:21], v[46:49], v[82:85], v[18:21]
	v_mfma_f32_16x16x32_bf16 v[22:25], v[58:61], v[82:85], v[22:25]
	v_mfma_f32_16x16x32_bf16 v[26:29], v[46:49], v[90:93], v[26:29]
	v_mfma_f32_16x16x32_bf16 v[30:33], v[58:61], v[90:93], v[30:33]
	s_waitcnt vmcnt(0)
	s_barrier
	v_add_u32_e32 v58, 0x1c000, v52
	v_add_u32_e32 v90, 0x18000, v51
	ds_read_b128 v[42:45], v58
	ds_read_b128 v[46:49], v58 offset:1024
	ds_read_b128 v[54:57], v58 offset:2048
	ds_read_b128 v[58:61], v58 offset:3072
	ds_read_b128 v[62:65], v90
	ds_read_b128 v[66:69], v90 offset:1024
	ds_read_b128 v[70:73], v90 offset:2048
	ds_read_b128 v[74:77], v90 offset:3072
	ds_read_b128 v[78:81], v90 offset:4096
	ds_read_b128 v[82:85], v90 offset:5120
	ds_read_b128 v[86:89], v90 offset:6144
	ds_read_b128 v[90:93], v90 offset:7168
	s_waitcnt lgkmcnt(0)
	s_waitcnt lgkmcnt(0)
	v_mfma_f32_16x16x32_bf16 v[2:5], v[42:45], v[62:65], v[2:5]
	v_mfma_f32_16x16x32_bf16 v[6:9], v[54:57], v[62:65], v[6:9]
	v_mfma_f32_16x16x32_bf16 v[10:13], v[42:45], v[70:73], v[10:13]
	v_mfma_f32_16x16x32_bf16 v[14:17], v[54:57], v[70:73], v[14:17]
	v_mfma_f32_16x16x32_bf16 v[18:21], v[42:45], v[78:81], v[18:21]
	v_mfma_f32_16x16x32_bf16 v[22:25], v[54:57], v[78:81], v[22:25]
	v_mfma_f32_16x16x32_bf16 v[26:29], v[42:45], v[86:89], v[26:29]
	v_mfma_f32_16x16x32_bf16 v[30:33], v[54:57], v[86:89], v[30:33]
	v_mfma_f32_16x16x32_bf16 v[2:5], v[46:49], v[66:69], v[2:5]
	v_mfma_f32_16x16x32_bf16 v[6:9], v[58:61], v[66:69], v[6:9]
	v_mfma_f32_16x16x32_bf16 v[10:13], v[46:49], v[74:77], v[10:13]
	v_mfma_f32_16x16x32_bf16 v[14:17], v[58:61], v[74:77], v[14:17]
	v_mfma_f32_16x16x32_bf16 v[18:21], v[46:49], v[82:85], v[18:21]
	v_mfma_f32_16x16x32_bf16 v[22:25], v[58:61], v[82:85], v[22:25]
	v_mfma_f32_16x16x32_bf16 v[26:29], v[46:49], v[90:93], v[26:29]
	v_mfma_f32_16x16x32_bf16 v[30:33], v[58:61], v[90:93], v[30:33]
	v_lshl_or_b32 v42, s2, 7, v53
	v_lshl_add_u32 v44, s8, 7, v50
	v_readlane_b32 s2, v254, 53
	v_ashrrev_i32_e32 v43, 31, v42
	v_readlane_b32 s3, v254, 54
	v_ashrrev_i32_e32 v45, 31, v44
	v_cvt_pk_bf16_f32 v2, v2, v3
	v_lshl_add_u64 v[42:43], v[42:43], 1, s[2:3]
	v_cvt_pk_bf16_f32 v3, v4, v5
	v_cvt_pk_bf16_f32 v4, v6, v7
	v_lshlrev_b64 v[6:7], 12, v[44:45]
	v_cvt_pk_bf16_f32 v5, v8, v9
	v_lshl_add_u64 v[6:7], v[42:43], 0, v[6:7]
	global_store_dwordx4 v[6:7], v[2:5], off
	v_or_b32_e32 v6, 16, v44
	v_ashrrev_i32_e32 v7, 31, v6
	v_lshlrev_b64 v[6:7], 12, v[6:7]
	v_cvt_pk_bf16_f32 v2, v10, v11
	v_cvt_pk_bf16_f32 v3, v12, v13
	v_cvt_pk_bf16_f32 v4, v14, v15
	v_cvt_pk_bf16_f32 v5, v16, v17
	v_lshl_add_u64 v[6:7], v[42:43], 0, v[6:7]
	global_store_dwordx4 v[6:7], v[2:5], off
	v_or_b32_e32 v6, 32, v44
	v_ashrrev_i32_e32 v7, 31, v6
	v_lshlrev_b64 v[6:7], 12, v[6:7]
	v_cvt_pk_bf16_f32 v2, v18, v19
	v_cvt_pk_bf16_f32 v3, v20, v21
	v_cvt_pk_bf16_f32 v4, v22, v23
	v_cvt_pk_bf16_f32 v5, v24, v25
	v_lshl_add_u64 v[6:7], v[42:43], 0, v[6:7]
	global_store_dwordx4 v[6:7], v[2:5], off
	v_or_b32_e32 v6, 48, v44
	v_ashrrev_i32_e32 v7, 31, v6
	v_lshlrev_b64 v[6:7], 12, v[6:7]
	s_add_i32 s7, s7, s20
	s_add_i32 s21, s21, s20
	v_cvt_pk_bf16_f32 v2, v26, v27
	v_cvt_pk_bf16_f32 v3, v28, v29
	v_cvt_pk_bf16_f32 v4, v30, v31
	v_cvt_pk_bf16_f32 v5, v32, v33
	v_lshl_add_u64 v[6:7], v[42:43], 0, v[6:7]
	s_cmp_gt_i32 s7, 63
	global_store_dwordx4 v[6:7], v[2:5], off
	s_barrier
	s_cbranch_scc0 .LBB0_503
